# prompt attention constant-bias tiles: bias loaded once per workgroup instead of per-tile LDS read + 38 copies (bit-identical)
# baseline (speedup 1.0000x reference)
.LBB0_434:
	s_lshl_b64 s[92:93], s[14:15], 1
	s_add_u32 s4, s70, s92
	s_mul_i32 s3, s68, 0xffffd300
	s_addc_u32 s5, s71, s93
	s_add_i32 s86, s58, s3
	s_mul_i32 s6, s14, 0x10800
	s_mul_hi_i32 s3, s14, 0x10800
	s_add_u32 s6, s76, s6
	v_readlane_b32 s36, v249, 57
	s_addc_u32 s7, s77, s3
	s_lshl_b64 s[8:9], s[14:15], 2
	v_readlane_b32 s40, v249, 61
	v_readlane_b32 s41, v249, 62
	s_add_u32 s8, s40, s8
	v_readlane_b32 s42, v249, 63
	s_addc_u32 s9, s41, s9
	v_readlane_b32 s43, v248, 0
	s_add_u32 s42, s12, s92
	s_getreg_b32 s3, hwreg(HW_REG_XCC_ID, 0, 4)
	s_addc_u32 s43, s13, s93
	s_and_b32 s3, s3, 7
	s_lshl_b32 s15, s3, 8
	s_add_u32 s40, s18, s15
	s_addc_u32 s41, s19, 0
	s_add_u32 s60, s24, 0x1a20400
	s_addc_u32 s61, s25, 0
	s_add_u32 s64, s24, 0x1a20500
	s_addc_u32 s65, s25, 0
	s_add_u32 s66, s24, 0x1a20600
	s_addc_u32 s67, s25, 0
	s_add_u32 s74, s24, 0x1a20700
	s_addc_u32 s75, s25, 0
	s_add_u32 s76, s24, 0x1a20800
	v_lshlrev_b32_e32 v0, 1, v185
	s_addc_u32 s77, s25, 0
	v_and_b32_e32 v226, 24, v0
	v_and_b32_e32 v227, 3, v152
	s_add_u32 s78, s24, 0x1a20900
	v_lshl_add_u64 v[188:189], s[4:5], 0, v[186:187]
	v_or_b32_e32 v228, v226, v227
	s_movk_i32 s4, 0xa00
	v_mov_b32_e32 v1, 0x2800
	s_addc_u32 s79, s25, 0
	v_mad_u32_u24 v2, v228, s4, v1
	v_mul_u32_u24_e32 v1, 0x8400, v185
	s_add_u32 s80, s24, 0x1a20a00
	v_mul_u32_u24_e32 v0, 0xa00, v228
	v_mov_b32_e32 v197, 0
	v_lshl_add_u64 v[190:191], s[6:7], 0, v[186:187]
	v_lshlrev_b32_e32 v196, 1, v1
	v_lshlrev_b32_e32 v4, 2, v153
	s_addc_u32 s81, s25, 0
	v_readlane_b32 s39, v249, 60
	v_lshl_add_u64 v[198:199], v[190:191], 0, v[196:197]
	v_ashrrev_i32_e32 v5, 31, v4
	s_add_u32 s82, s24, 0x1a20b00
	v_lshlrev_b32_e32 v196, 1, v0
	s_mov_b32 s39, 0
	v_sub_u32_e32 v229, v82, v185
	v_cmp_gt_u32_e64 s[6:7], 16, v152
	v_lshl_add_u32 v224, v152, 2, s69
	v_lshl_add_u64 v[192:193], v[4:5], 2, s[8:9]
	v_lshl_add_u32 v225, v185, 2, 0
	v_lshl_add_u64 v[194:195], v[4:5], 1, s[42:43]
	s_addc_u32 s83, s25, 0
	v_lshl_add_u64 v[200:201], v[188:189], 0, v[196:197]
	v_lshlrev_b32_e32 v202, 1, v2
	v_lshlrev_b32_e32 v204, 1, v0
	s_movk_i32 s15, 0xff80
	v_mov_b32_e32 v230, 0x358637bd
	v_mov_b32_e32 v231, 0x1400
	v_readlane_b32 s37, v249, 58
	v_readlane_b32 s38, v249, 59
	v_readlane_b32 s44, v248, 1
	v_readlane_b32 s45, v248, 2
	v_readlane_b32 s46, v248, 3
	v_readlane_b32 s47, v248, 4
	v_readlane_b32 s48, v248, 5
	v_readlane_b32 s49, v248, 6
	v_readlane_b32 s50, v248, 7
	v_readlane_b32 s51, v248, 8
	v_mov_b32_e32 v238, s86
	ds_read_b32 v238, v238
	s_waitcnt lgkmcnt(0)
	v_mov_b32_e32 v239, v238
	s_branch .LBB0_436

.LBB0_457:
	s_andn2_b64 vcc, exec, s[8:9]
	s_cbranch_vccnz .LBB0_459
	s_nop 3
	v_pk_add_f32 v[154:155], v[154:155], v[238:239]
	v_pk_add_f32 v[164:165], v[142:143], v[238:239]
	v_pk_add_f32 v[158:159], v[158:159], v[238:239]
	v_pk_add_f32 v[156:157], v[156:157], v[238:239]
	v_pk_add_f32 v[144:145], v[144:145], v[238:239]
	v_pk_add_f32 v[166:167], v[140:141], v[238:239]
	v_pk_add_f32 v[140:141], v[130:131], v[238:239]
	v_max_f32_e32 v130, v164, v165
	v_pk_add_f32 v[152:153], v[152:153], v[238:239]
	v_pk_add_f32 v[160:161], v[138:139], v[238:239]
	v_pk_add_f32 v[142:143], v[128:129], v[238:239]
	v_max_f32_e32 v128, v156, v157
	v_max_f32_e32 v129, v158, v159
	v_max3_f32 v130, v166, v167, v130
	v_pk_add_f32 v[162:163], v[136:137], v[238:239]
	v_max3_f32 v131, v128, v129, v130
	v_add_f32_e32 v128, 0x41000000, v233
	v_max_f32_e32 v130, v160, v161
	v_pk_add_f32 v[136:137], v[134:135], v[238:239]
	v_cmp_gt_f32_e32 vcc, v131, v128
	v_max_f32_e32 v128, v152, v153
	v_max_f32_e32 v129, v154, v155
	v_max3_f32 v130, v162, v163, v130
	v_pk_add_f32 v[150:151], v[150:151], v[238:239]
	v_pk_add_f32 v[148:149], v[148:149], v[238:239]
	v_pk_add_f32 v[138:139], v[132:133], v[238:239]
	v_max3_f32 v130, v128, v129, v130
	v_add_f32_e32 v128, 0x41000000, v232
	v_max_f32_e32 v132, v136, v137
	v_cmp_gt_f32_e64 s[8:9], v130, v128
	v_max_f32_e32 v128, v148, v149
	v_max_f32_e32 v129, v150, v151
	v_max3_f32 v132, v138, v139, v132
	v_pk_add_f32 v[146:147], v[146:147], v[238:239]
	v_max3_f32 v129, v128, v129, v132
	v_add_f32_e32 v128, 0x41000000, v205
	v_max_f32_e32 v133, v140, v141
	s_or_b64 s[8:9], vcc, s[8:9]
	v_cmp_gt_f32_e32 vcc, v129, v128
	v_max_f32_e32 v128, v144, v145
	v_max_f32_e32 v132, v146, v147
	v_max3_f32 v133, v142, v143, v133
	v_max3_f32 v128, v128, v132, v133
	v_add_f32_e32 v132, 0x41000000, v203
	s_or_b64 s[8:9], s[8:9], vcc
	v_cmp_gt_f32_e32 vcc, v128, v132
	s_or_b64 vcc, s[8:9], vcc
	s_cbranch_vccz .LBB0_461
	s_branch .Lattb_460

.Lattb_460:
	ds_bpermute_b32 v132, v222, v131
	v_max_f32_e32 v131, v131, v131
	s_waitcnt lgkmcnt(0)
	v_max_f32_e32 v132, v132, v132
	v_max_f32_e32 v131, v131, v132
	ds_bpermute_b32 v132, v223, v131
	s_waitcnt lgkmcnt(0)
	v_max3_f32 v134, v233, v131, v132
	v_sub_f32_e32 v131, v233, v134
	v_exp_f32_e32 v132, v131
	ds_bpermute_b32 v131, v222, v130
	v_max_f32_e32 v130, v130, v130
	v_mov_b32_e32 v233, v134
	v_pk_mul_f32 v[94:95], v[94:95], v[132:133] op_sel_hi:[1,0]
	v_pk_mul_f32 v[92:93], v[92:93], v[132:133] op_sel_hi:[1,0]
	s_waitcnt lgkmcnt(0)
	v_max_f32_e32 v131, v131, v131
	v_max_f32_e32 v130, v130, v131
	ds_bpermute_b32 v131, v223, v130
	v_pk_mul_f32 v[90:91], v[90:91], v[132:133] op_sel_hi:[1,0]
	v_pk_mul_f32 v[88:89], v[88:89], v[132:133] op_sel_hi:[1,0]
	v_pk_mul_f32 v[86:87], v[86:87], v[132:133] op_sel_hi:[1,0]
	v_pk_mul_f32 v[84:85], v[84:85], v[132:133] op_sel_hi:[1,0]
	s_waitcnt lgkmcnt(0)
	v_max3_f32 v135, v232, v130, v131
	v_sub_f32_e32 v130, v232, v135
	v_pk_mul_f32 v[82:83], v[82:83], v[132:133] op_sel_hi:[1,0]
	v_pk_mul_f32 v[80:81], v[80:81], v[132:133] op_sel_hi:[1,0]
	v_exp_f32_e32 v133, v130
	v_mov_b32_e32 v232, v135
	v_mov_b32_e32 v130, v133
	v_pk_mul_f32 v[42:43], v[42:43], v[130:131] op_sel_hi:[1,0]
	v_pk_mul_f32 v[40:41], v[40:41], v[130:131] op_sel_hi:[1,0]
	v_pk_mul_f32 v[46:47], v[46:47], v[130:131] op_sel_hi:[1,0]
	v_pk_mul_f32 v[44:45], v[44:45], v[130:131] op_sel_hi:[1,0]
	v_pk_mul_f32 v[38:39], v[38:39], v[130:131] op_sel_hi:[1,0]
	v_pk_mul_f32 v[36:37], v[36:37], v[130:131] op_sel_hi:[1,0]
	v_pk_mul_f32 v[34:35], v[34:35], v[130:131] op_sel_hi:[1,0]
	v_pk_mul_f32 v[32:33], v[32:33], v[130:131] op_sel_hi:[1,0]
	ds_bpermute_b32 v130, v222, v129
	v_max_f32_e32 v129, v129, v129
	v_pk_mul_f32 v[208:209], v[208:209], v[132:133]
	s_waitcnt lgkmcnt(0)
	v_max_f32_e32 v130, v130, v130
	v_max_f32_e32 v129, v129, v130
	ds_bpermute_b32 v130, v223, v129
	s_waitcnt lgkmcnt(0)
	v_max3_f32 v129, v205, v129, v130
	v_sub_f32_e32 v130, v205, v129
	v_exp_f32_e32 v130, v130
	v_mov_b32_e32 v205, v129
	v_pk_mul_f32 v[26:27], v[26:27], v[130:131] op_sel_hi:[1,0]
	v_pk_mul_f32 v[24:25], v[24:25], v[130:131] op_sel_hi:[1,0]
	v_pk_mul_f32 v[30:31], v[30:31], v[130:131] op_sel_hi:[1,0]
	v_pk_mul_f32 v[28:29], v[28:29], v[130:131] op_sel_hi:[1,0]
	v_pk_mul_f32 v[22:23], v[22:23], v[130:131] op_sel_hi:[1,0]
	v_pk_mul_f32 v[20:21], v[20:21], v[130:131] op_sel_hi:[1,0]
	v_pk_mul_f32 v[18:19], v[18:19], v[130:131] op_sel_hi:[1,0]
	v_pk_mul_f32 v[16:17], v[16:17], v[130:131] op_sel_hi:[1,0]
	ds_bpermute_b32 v131, v222, v128
	v_max_f32_e32 v128, v128, v128
	s_waitcnt lgkmcnt(0)
	v_max_f32_e32 v131, v131, v131
	v_max_f32_e32 v128, v128, v131
	ds_bpermute_b32 v131, v223, v128
	s_waitcnt lgkmcnt(0)
	v_max3_f32 v132, v203, v128, v131
	v_sub_f32_e32 v128, v203, v132
	v_exp_f32_e32 v131, v128
	v_mov_b32_e32 v203, v132
	v_mov_b32_e32 v128, v131
	v_pk_mul_f32 v[206:207], v[206:207], v[130:131]
	v_pk_mul_f32 v[6:7], v[6:7], v[128:129] op_sel_hi:[1,0]
	v_pk_mul_f32 v[4:5], v[4:5], v[128:129] op_sel_hi:[1,0]
	v_pk_mul_f32 v[14:15], v[14:15], v[128:129] op_sel_hi:[1,0]
	v_pk_mul_f32 v[12:13], v[12:13], v[128:129] op_sel_hi:[1,0]
	v_pk_mul_f32 v[10:11], v[10:11], v[128:129] op_sel_hi:[1,0]
	v_pk_mul_f32 v[8:9], v[8:9], v[128:129] op_sel_hi:[1,0]
	v_pk_mul_f32 v[2:3], v[2:3], v[128:129] op_sel_hi:[1,0]
	v_pk_mul_f32 v[0:1], v[0:1], v[128:129] op_sel_hi:[1,0]
